# combine phase: gate (gg) load issued together with the conv-input loads (one wait instead of two); with v39 this makes 2 instead of 4 serialized round trips per pass
# speedup vs baseline: 1.0190x; 1.0049x over previous
; __device__ __forceinline__ unsigned pk2(float lo, float hi) { unsigned r; asm("v_cvt_pk_bf16_f32 %0, %1, %2" : "=v"(r) : "v"(lo), "v"(hi)); return r; }
; __device__ __forceinline__ float bf_lo(unsigned u) { return __uint_as_float(u << 16); }
; __device__ __forceinline__ float bf_hi(unsigned u) { return __uint_as_float(u & 0xffff0000u); }
; __device__ __forceinline__ void phase_combine(const Params& P, int layer_i) {
;     ...
;             const u32x4 gg = *(const u32x4*)(gz + row * AW + col);
;             u32x4 yb;
; #pragma unroll
;             for (int e = 0; e < 4; ++e) {
;                 const float lo = bf_lo(gg[e]) * (w0[2 * e] * bf_lo(pm[e]) + w1[2 * e] * bf_lo(pc[e]) + w2[2 * e] * bf_lo(pn[e]));
;                 const float hi = bf_hi(gg[e]) * (w0[2 * e + 1] * bf_hi(pm[e]) + w1[2 * e + 1] * bf_hi(pc[e]) + w2[2 * e + 1] * bf_hi(pn[e]));
;                 yb[e] = pk2(lo, hi); }
;             *(u32x4*)(Y + row * DM + AW + col) = yb;
.LBB0_254:
	s_or_b64 exec, exec, s[24:25]
	v_add_co_u32_e32 v32, vcc, 0x176e4000, v56
	s_nop 1
	v_addc_co_u32_e32 v33, vcc, 0, v57, vcc
	global_load_dwordx4 v[56:59], v[32:33], off
	s_waitcnt vmcnt(0) lgkmcnt(0)
	v_lshlrev_b32_e32 v35, 16, v26
	v_lshlrev_b32_e32 v33, 16, v22
	v_lshlrev_b32_e32 v32, 16, v18
	v_pk_mul_f32 v[32:33], v[54:55], v[32:33]
	v_and_b32_e32 v26, 0xffff0000, v26
	v_fma_f32 v32, v10, v35, v32
	v_add_f32_e32 v32, v32, v33
	v_and_b32_e32 v33, 0xffff0000, v22
	v_lshlrev_b32_e32 v22, 16, v27
	v_and_b32_e32 v27, 0xffff0000, v27
	s_add_i32 s6, s6, 64
	v_lshl_add_u64 v[36:37], v[36:37], 0, s[34:35]
	v_lshl_add_u64 v[38:39], v[38:39], 0, s[28:29]
	v_lshl_add_u64 v[40:41], v[40:41], 0, s[38:39]
	v_lshl_add_u64 v[42:43], v[42:43], 0, s[34:35]
	v_lshl_add_u64 v[44:45], v[44:45], 0, s[28:29]
	v_lshl_add_u64 v[46:47], v[46:47], 0, s[38:39]
	s_cmpk_eq_i32 s6, 0x200
	s_waitcnt vmcnt(0) lgkmcnt(0)
	v_lshlrev_b32_e32 v0, 16, v56
	v_mul_f32_e32 v0, v32, v0
	v_and_b32_e32 v32, 0xffff0000, v18
	v_pk_mul_f32 v[32:33], v[6:7], v[32:33]
	v_and_b32_e32 v35, 0xffff0000, v56
	v_fma_f32 v18, v11, v26, v32
	v_add_f32_e32 v18, v18, v33
	v_lshlrev_b32_e32 v33, 16, v23
	v_lshlrev_b32_e32 v32, 16, v19
	v_pk_mul_f32 v[32:33], v[52:53], v[32:33]
	v_mul_f32_e32 v18, v18, v35
	v_fma_f32 v22, v12, v22, v32
	v_cvt_pk_bf16_f32 v18, v0, v18
	v_lshlrev_b32_e32 v0, 16, v57
	v_add_f32_e32 v22, v22, v33
	v_mul_f32_e32 v0, v22, v0
	v_and_b32_e32 v23, 0xffff0000, v23
	v_and_b32_e32 v22, 0xffff0000, v19
	v_pk_mul_f32 v[22:23], v[8:9], v[22:23]
	v_and_b32_e32 v26, 0xffff0000, v57
	v_fma_f32 v19, v13, v27, v22
	v_add_f32_e32 v19, v19, v23
	v_lshlrev_b32_e32 v23, 16, v24
	v_lshlrev_b32_e32 v22, 16, v20
	v_mul_f32_e32 v19, v19, v26
	v_lshlrev_b32_e32 v26, 16, v28
	v_pk_mul_f32 v[22:23], v[50:51], v[22:23]
	v_cvt_pk_bf16_f32 v19, v0, v19
	v_lshlrev_b32_e32 v0, 16, v58
	v_fma_f32 v22, v14, v26, v22
	v_add_f32_e32 v22, v22, v23
	v_mul_f32_e32 v0, v22, v0
	v_and_b32_e32 v23, 0xffff0000, v24
	v_and_b32_e32 v22, 0xffff0000, v20
	v_and_b32_e32 v27, 0xffff0000, v28
	v_pk_mul_f32 v[22:23], v[2:3], v[22:23]
	v_and_b32_e32 v26, 0xffff0000, v58
	v_fma_f32 v20, v15, v27, v22
	v_add_f32_e32 v20, v20, v23
	v_lshlrev_b32_e32 v23, 16, v25
	v_lshlrev_b32_e32 v22, 16, v21
	v_lshlrev_b32_e32 v24, 16, v29
	v_pk_mul_f32 v[22:23], v[48:49], v[22:23]
	v_mul_f32_e32 v20, v20, v26
	v_fma_f32 v22, v16, v24, v22
	v_cvt_pk_bf16_f32 v20, v0, v20
	v_lshlrev_b32_e32 v0, 16, v59
	v_add_f32_e32 v22, v22, v23
	v_mul_f32_e32 v0, v22, v0
	v_and_b32_e32 v23, 0xffff0000, v25
	v_and_b32_e32 v22, 0xffff0000, v21
	v_and_b32_e32 v26, 0xffff0000, v29
	v_pk_mul_f32 v[22:23], v[4:5], v[22:23]
	v_and_b32_e32 v24, 0xffff0000, v59
	v_fma_f32 v21, v17, v26, v22
	v_add_f32_e32 v21, v21, v23
	v_add_co_u32_e32 v22, vcc, 0x96e4000, v30
	v_mul_f32_e32 v21, v21, v24
	s_nop 0
	v_addc_co_u32_e32 v23, vcc, 0, v31, vcc
	v_cvt_pk_bf16_f32 v21, v0, v21
	global_store_dwordx4 v[22:23], v[18:21], off offset:2048
	s_cbranch_scc1 .LBB0_252

; __device__ __forceinline__ unsigned pk2(float lo, float hi) { unsigned r; asm("v_cvt_pk_bf16_f32 %0, %1, %2" : "=v"(r) : "v"(lo), "v"(hi)); return r; }
; __device__ __forceinline__ float bf_lo(unsigned u) { return __uint_as_float(u << 16); }
; __device__ __forceinline__ float bf_hi(unsigned u) { return __uint_as_float(u & 0xffff0000u); }
; __device__ __forceinline__ float fexp2(float x) { return __builtin_amdgcn_exp2f(x); }
; __device__ __forceinline__ void phase_combine(const Params& P, int layer_i) {
;     ...
;             const int pos = s0 + pass * 32 + (tid2 >> 4); const size_t row = (size_t)b * SEQ + pos;
;             const float l0 = Lse[row * 8 + hh], l1 = Lse[(size_t)MTOK * 8 + row * 8 + hh], l2 = Lse[(size_t)2 * MTOK * 8 + row * 8 + hh];
;             const float lm = fmaxf(l0, fmaxf(l1, l2));
;             float e0 = fexp2((l0 - lm) * 1.4426950408889634f), e1 = fexp2((l1 - lm) * 1.4426950408889634f), e2 = fexp2((l2 - lm) * 1.4426950408889634f);
;             const float ei = 1.f / (e0 + e1 + e2); e0 *= ei; e1 *= ei; e2 *= ei;
;             const u32x4 a0 = *(const u32x4*)(Op + row * AW + col), a1 = *(const u32x4*)(Op + (size_t)MTOK * AW + row * AW + col), a2 = *(const u32x4*)(Op + (size_t)2 * MTOK * AW + row * AW + col);
;             const u32x4 zz = *(const u32x4*)(sza + row * AW + col);
;     ...
;             const u32x4 gg = *(const u32x4*)(gz + row * AW + col);
;             u32x4 yb;
; #pragma unroll
;             for (int e = 0; e < 4; ++e) {
;                 const float lo = bf_lo(gg[e]) * (w0[2 * e] * bf_lo(pm[e]) + w1[2 * e] * bf_lo(pc[e]) + w2[2 * e] * bf_lo(pn[e]));
;                 const float hi = bf_hi(gg[e]) * (w0[2 * e + 1] * bf_hi(pm[e]) + w1[2 * e + 1] * bf_hi(pc[e]) + w2[2 * e + 1] * bf_hi(pn[e]));
;                 yb[e] = pk2(lo, hi); }
;             *(u32x4*)(Y + row * DM + AW + col) = yb;
.LBB0_259:
	s_or_b64 exec, exec, s[24:25]
	v_add_co_u32_e32 v32, vcc, 0x176e4000, v56
	s_nop 1
	v_addc_co_u32_e32 v33, vcc, 0, v57, vcc
	global_load_dwordx4 v[56:59], v[32:33], off
	s_waitcnt vmcnt(0) lgkmcnt(0)
	v_lshlrev_b32_e32 v63, 16, v26
	v_lshlrev_b32_e32 v33, 16, v22
	v_lshlrev_b32_e32 v32, 16, v18
	v_pk_mul_f32 v[32:33], v[54:55], v[32:33]
	v_and_b32_e32 v26, 0xffff0000, v26
	v_fma_f32 v32, v10, v63, v32
	v_add_f32_e32 v32, v32, v33
	v_and_b32_e32 v33, 0xffff0000, v22
	s_mov_b32 s2, 0x1f6e4000
	v_add_u32_e32 v0, 32, v0
	s_waitcnt vmcnt(0) lgkmcnt(0)
	v_lshlrev_b32_e32 v35, 16, v56
	v_mul_f32_e32 v35, v32, v35
	v_and_b32_e32 v32, 0xffff0000, v18
	v_pk_mul_f32 v[32:33], v[6:7], v[32:33]
	v_lshlrev_b32_e32 v22, 16, v57
	v_fma_f32 v18, v11, v26, v32
	v_add_f32_e32 v18, v18, v33
	v_lshlrev_b32_e32 v33, 16, v23
	v_lshlrev_b32_e32 v32, 16, v19
	v_lshlrev_b32_e32 v26, 16, v27
	v_pk_mul_f32 v[32:33], v[52:53], v[32:33]
	v_and_b32_e32 v23, 0xffff0000, v23
	v_fma_f32 v26, v12, v26, v32
	v_add_f32_e32 v26, v26, v33
	v_mul_f32_e32 v26, v26, v22
	v_and_b32_e32 v22, 0xffff0000, v19
	v_and_b32_e32 v27, 0xffff0000, v27
	v_pk_mul_f32 v[22:23], v[8:9], v[22:23]
	v_and_b32_e32 v32, 0xffff0000, v57
	v_fma_f32 v19, v13, v27, v22
	v_add_f32_e32 v19, v19, v23
	v_lshlrev_b32_e32 v23, 16, v24
	v_lshlrev_b32_e32 v22, 16, v20
	v_lshlrev_b32_e32 v27, 16, v28
	v_pk_mul_f32 v[22:23], v[50:51], v[22:23]
	v_mul_f32_e32 v19, v19, v32
	v_fma_f32 v22, v14, v27, v22
	v_cvt_pk_bf16_f32 v19, v26, v19
	v_lshlrev_b32_e32 v26, 16, v58
	v_add_f32_e32 v22, v22, v23
	v_mul_f32_e32 v26, v22, v26
	v_and_b32_e32 v23, 0xffff0000, v24
	v_and_b32_e32 v22, 0xffff0000, v20
	v_and_b32_e32 v28, 0xffff0000, v28
	v_pk_mul_f32 v[22:23], v[2:3], v[22:23]
	v_and_b32_e32 v27, 0xffff0000, v58
	v_fma_f32 v20, v15, v28, v22
	v_add_f32_e32 v20, v20, v23
	v_mul_f32_e32 v20, v20, v27
	v_lshlrev_b32_e32 v23, 16, v25
	v_lshlrev_b32_e32 v22, 16, v21
	v_cvt_pk_bf16_f32 v20, v26, v20
	v_lshlrev_b32_e32 v26, 16, v29
	v_pk_mul_f32 v[22:23], v[48:49], v[22:23]
	v_lshlrev_b32_e32 v24, 16, v59
	v_fma_f32 v22, v16, v26, v22
	v_add_f32_e32 v22, v22, v23
	v_mul_f32_e32 v24, v22, v24
	v_and_b32_e32 v23, 0xffff0000, v25
	v_and_b32_e32 v22, 0xffff0000, v21
	v_and_b32_e32 v27, 0xffff0000, v29
	v_pk_mul_f32 v[22:23], v[4:5], v[22:23]
	v_and_b32_e32 v56, 0xffff0000, v56
	v_fma_f32 v21, v17, v27, v22
	v_mul_f32_e32 v18, v18, v56
	v_and_b32_e32 v26, 0xffff0000, v59
	v_add_f32_e32 v21, v21, v23
	v_add_co_u32_e32 v22, vcc, s83, v30
	v_cvt_pk_bf16_f32 v18, v35, v18
	v_mul_f32_e32 v21, v21, v26
	s_nop 0
	v_addc_co_u32_e32 v23, vcc, 0, v31, vcc
	v_cvt_pk_bf16_f32 v21, v24, v21
	global_store_dwordx4 v[22:23], v[18:21], off offset:2048
	v_lshl_add_u64 v[56:57], s[12:13], 0, v[36:37]
	s_nop 0
	v_lshl_add_u64 v[18:19], s[12:13], 0, v[40:41]
	v_add_co_u32_e32 v20, vcc, s2, v18
	s_mov_b32 s2, 0x1f764000
	s_nop 0
	v_addc_co_u32_e32 v21, vcc, 0, v19, vcc
	global_load_dword v79, v[20:21], off
	v_add_co_u32_e32 v20, vcc, s2, v18
	s_mov_b32 s2, 0x1f7e4000
	s_nop 0
	v_addc_co_u32_e32 v21, vcc, 0, v19, vcc
	v_add_co_u32_e32 v18, vcc, s2, v18
	global_load_dword v77, v[20:21], off
	s_nop 0
	v_addc_co_u32_e32 v19, vcc, 0, v19, vcc
	global_load_dword v75, v[18:19], off
	v_add_co_u32_e32 v18, vcc, s79, v56
	s_nop 0
	v_addc_co_u32_e32 v19, vcc, 0, v57, vcc
	v_add_co_u32_e32 v22, vcc, s80, v56
	global_load_dwordx4 v[18:21], v[18:19], off
	s_nop 0
	v_addc_co_u32_e32 v23, vcc, 0, v57, vcc
	v_add_co_u32_e32 v26, vcc, s81, v56
	global_load_dwordx4 v[22:25], v[22:23], off
	s_nop 0
	v_addc_co_u32_e32 v27, vcc, 0, v57, vcc
	v_add_co_u32_e32 v30, vcc, s82, v56
	global_load_dwordx4 v[26:29], v[26:27], off
	s_nop 0
	v_addc_co_u32_e32 v31, vcc, 0, v57, vcc
	global_load_dwordx4 v[30:33], v[30:31], off
	s_waitcnt vmcnt(4) lgkmcnt(0)
; __device__ __forceinline__ unsigned pk2(float lo, float hi) { unsigned r; asm("v_cvt_pk_bf16_f32 %0, %1, %2" : "=v"(r) : "v"(lo), "v"(hi)); return r; }
; __device__ __forceinline__ float bf_lo(unsigned u) { return __uint_as_float(u << 16); }
; __device__ __forceinline__ float bf_hi(unsigned u) { return __uint_as_float(u & 0xffff0000u); }
; __device__ __forceinline__ float fexp2(float x) { return __builtin_amdgcn_exp2f(x); }
; __device__ __forceinline__ void phase_combine(const Params& P, int layer_i) {
;     ...
;             const float l0 = Lse[row * 8 + hh], l1 = Lse[(size_t)MTOK * 8 + row * 8 + hh], l2 = Lse[(size_t)2 * MTOK * 8 + row * 8 + hh];
;             const float lm = fmaxf(l0, fmaxf(l1, l2));
;             float e0 = fexp2((l0 - lm) * 1.4426950408889634f), e1 = fexp2((l1 - lm) * 1.4426950408889634f), e2 = fexp2((l2 - lm) * 1.4426950408889634f);
;             const float ei = 1.f / (e0 + e1 + e2); e0 *= ei; e1 *= ei; e2 *= ei;
;             const u32x4 a0 = *(const u32x4*)(Op + row * AW + col), a1 = *(const u32x4*)(Op + (size_t)MTOK * AW + row * AW + col), a2 = *(const u32x4*)(Op + (size_t)2 * MTOK * AW + row * AW + col);
;             const u32x4 zz = *(const u32x4*)(sza + row * AW + col);
;             u32x4 ya;
; #pragma unroll
;             for (int e = 0; e < 4; ++e) {
;                 const float lo = (e0 * bf_lo(a0[e]) + e1 * bf_lo(a1[e]) + e2 * bf_lo(a2[e])) * bf_lo(zz[e]);
;                 const float hi = (e0 * bf_hi(a0[e]) + e1 * bf_hi(a1[e]) + e2 * bf_hi(a2[e])) * bf_hi(zz[e]);
;                 ya[e] = pk2(lo, hi); }
;             *(u32x4*)(Y + row * DM + col) = ya;
;             const u32x4 pc = *(const u32x4*)(pp + row * AW + col);
;             u32x4 pm = (u32x4){0u, 0u, 0u, 0u}, pn = (u32x4){0u, 0u, 0u, 0u};
;             if (pos > 0) pm = *(const u32x4*)(pp + (row - 1) * AW + col);
;             if (pos < SEQ - 1) pn = *(const u32x4*)(pp + (row + 1) * AW + col);
	v_max3_f32 v76, v79, v77, v75
	v_sub_f32_e32 v78, v79, v76
	v_sub_f32_e32 v77, v77, v76
	v_mul_f32_e32 v78, 0x3fb8aa3b, v78
	v_mul_f32_e32 v77, 0x3fb8aa3b, v77
	v_sub_f32_e32 v75, v75, v76
	v_exp_f32_e32 v59, v78
	v_exp_f32_e32 v77, v77
	v_mul_f32_e32 v75, 0x3fb8aa3b, v75
	v_exp_f32_e32 v58, v75
	v_add_f32_e32 v75, v59, v77
	v_add_f32_e32 v75, v58, v75
	v_div_scale_f32 v76, s[2:3], v75, v75, 1.0
	v_rcp_f32_e32 v78, v76
	s_nop 0
	v_fma_f32 v79, -v76, v78, 1.0
	v_fmac_f32_e32 v78, v79, v78
	v_div_scale_f32 v79, vcc, 1.0, v75, 1.0
	v_mul_f32_e32 v80, v79, v78
	v_fma_f32 v81, -v76, v80, v79
	v_fmac_f32_e32 v80, v81, v78
	v_fma_f32 v76, -v76, v80, v79
	v_div_fmas_f32 v76, v76, v78, v80
	v_div_fixup_f32 v64, v76, v75, 1.0
	v_mul_f32_e32 v35, v77, v64
	s_waitcnt vmcnt(0) lgkmcnt(0)
	v_lshlrev_b32_e32 v63, 16, v22
	v_and_b32_e32 v66, 0xffff0000, v22
	v_lshlrev_b32_e32 v68, 16, v23
	v_and_b32_e32 v70, 0xffff0000, v23
	v_lshlrev_b32_e32 v72, 16, v24
	v_and_b32_e32 v24, 0xffff0000, v24
	v_lshlrev_b32_e32 v74, 16, v25
	v_lshlrev_b32_e32 v65, 16, v30
	v_and_b32_e32 v67, 0xffff0000, v30
	v_lshlrev_b32_e32 v69, 16, v31
	v_and_b32_e32 v71, 0xffff0000, v31
	v_pk_mul_f32 v[22:23], v[58:59], v[64:65] op_sel_hi:[1,0]
	v_lshlrev_b32_e32 v31, 16, v18
	v_lshlrev_b32_e32 v30, 16, v26
	v_pk_mul_f32 v[30:31], v[22:23], v[30:31]
	v_lshlrev_b32_e32 v73, 16, v32
	v_fma_f32 v31, v35, v63, v31
	v_add_f32_e32 v30, v30, v31
	v_mul_f32_e32 v58, v30, v65
	v_and_b32_e32 v31, 0xffff0000, v18
	v_and_b32_e32 v30, 0xffff0000, v26
	v_pk_mul_f32 v[30:31], v[22:23], v[30:31]
	v_and_b32_e32 v32, 0xffff0000, v32
	v_fma_f32 v18, v35, v66, v31
	v_add_f32_e32 v18, v30, v18
	v_lshlrev_b32_e32 v31, 16, v19
	v_lshlrev_b32_e32 v30, 16, v27
	v_pk_mul_f32 v[30:31], v[22:23], v[30:31]
	v_mul_f32_e32 v18, v18, v67
	v_fma_f32 v26, v35, v68, v31
	v_add_f32_e32 v26, v30, v26
	v_and_b32_e32 v31, 0xffff0000, v19
	v_and_b32_e32 v30, 0xffff0000, v27
	v_cvt_pk_bf16_f32 v18, v58, v18
	v_mul_f32_e32 v58, v26, v69
	v_pk_mul_f32 v[26:27], v[22:23], v[30:31]
	s_nop 0
	v_fma_f32 v19, v35, v70, v27
	v_add_f32_e32 v19, v26, v19
	v_lshlrev_b32_e32 v27, 16, v20
	v_lshlrev_b32_e32 v26, 16, v28
	v_pk_mul_f32 v[26:27], v[22:23], v[26:27]
	v_mul_f32_e32 v19, v19, v71
	v_fma_f32 v27, v35, v72, v27
	v_add_f32_e32 v26, v26, v27
	v_mul_f32_e32 v30, v26, v73
	v_and_b32_e32 v27, 0xffff0000, v20
	v_and_b32_e32 v26, 0xffff0000, v28
	v_pk_mul_f32 v[26:27], v[22:23], v[26:27]
	v_cvt_pk_bf16_f32 v19, v58, v19
	v_mov_b32_e32 v28, 0
	v_fma_f32 v20, v35, v24, v27
	v_add_f32_e32 v20, v26, v20
	v_lshlrev_b32_e32 v27, 16, v21
	v_lshlrev_b32_e32 v26, 16, v29
	v_pk_mul_f32 v[26:27], v[22:23], v[26:27]
	v_mul_f32_e32 v20, v20, v32
	v_fma_f32 v24, v35, v74, v27
	v_add_f32_e32 v24, v26, v24
	v_lshlrev_b32_e32 v26, 16, v33
	v_mul_f32_e32 v26, v24, v26
	v_and_b32_e32 v27, 0xffff0000, v25
	v_and_b32_e32 v25, 0xffff0000, v21
	v_and_b32_e32 v24, 0xffff0000, v29
	v_pk_mul_f32 v[22:23], v[22:23], v[24:25]
	v_cvt_pk_bf16_f32 v20, v30, v20
	v_lshl_add_u64 v[30:31], s[12:13], 0, v[38:39]
	v_fma_f32 v21, v35, v27, v23
	v_add_f32_e32 v21, v22, v21
	v_and_b32_e32 v22, 0xffff0000, v33
	v_mul_f32_e32 v21, v21, v22
	v_add_co_u32_e32 v22, vcc, 0x96e4000, v30
	v_cvt_pk_bf16_f32 v21, v26, v21
	v_mov_b32_e32 v26, 0
	s_nop 0
	v_addc_co_u32_e32 v23, vcc, 0, v31, vcc
	global_store_dwordx4 v[22:23], v[18:21], off
	v_mov_b32_e32 v22, 0
	v_mov_b32_e32 v27, 0
	v_add_co_u32_e32 v18, vcc, 0x156e4000, v56
	v_mov_b32_e32 v29, 0
	s_nop 0
	v_addc_co_u32_e32 v19, vcc, 0, v57, vcc
	global_load_dwordx4 v[18:21], v[18:19], off
	v_cmp_lt_i32_e32 vcc, 0, v0
	s_and_saveexec_b64 s[24:25], vcc
	s_cbranch_execz .LBB0_261
	v_add_co_u32_e32 v24, vcc, 0x156e3000, v56
	s_nop 1
	v_addc_co_u32_e32 v25, vcc, 0, v57, vcc
	global_load_dwordx4 v[26:29], v[24:25], off offset:2048
